# prologue x->bf16+sumsq row loop: the 8 row-chunk loads issued together with counted waits instead of one load per full drain
# speedup vs baseline: 1.0067x; 1.0067x over previous
.LBB0_57:
	v_add_co_u32_e32 v24, vcc, 0xfffff000, v4
	v_lshl_add_u64 v[6:7], s[14:15], 0, v[2:3]
	s_nop 0
	v_addc_co_u32_e32 v25, vcc, -1, v5, vcc
	s_waitcnt lgkmcnt(0)
	global_load_dwordx4 v[176:179], v[24:25], off offset:-3072 nt
	global_load_dwordx4 v[180:183], v[24:25], off offset:-2048 nt
	global_load_dwordx4 v[184:187], v[24:25], off offset:-1024 nt
	global_load_dwordx4 v[188:191], v[4:5], off offset:-4096 nt
	global_load_dwordx4 v[192:195], v[4:5], off offset:-3072 nt
	global_load_dwordx4 v[196:199], v[4:5], off offset:-2048 nt
	global_load_dwordx4 v[200:203], v[4:5], off offset:-1024 nt
	global_load_dwordx4 v[204:207], v[4:5], off nt
	v_add_co_u32_e32 v6, vcc, s13, v6
	s_nop 1
	v_addc_co_u32_e32 v7, vcc, 0, v7, vcc
	s_waitcnt vmcnt(7)
	v_and_b32_sdwa v17, v179, v14 dst_sel:DWORD dst_unused:UNUSED_PAD src0_sel:WORD_1 src1_sel:DWORD
	v_and_b32_sdwa v18, v177, v14 dst_sel:DWORD dst_unused:UNUSED_PAD src0_sel:WORD_1 src1_sel:DWORD
	v_and_b32_sdwa v15, v178, v14 dst_sel:DWORD dst_unused:UNUSED_PAD src0_sel:WORD_1 src1_sel:DWORD
	v_and_b32_sdwa v16, v176, v14 dst_sel:DWORD dst_unused:UNUSED_PAD src0_sel:WORD_1 src1_sel:DWORD
	v_add3_u32 v17, v179, v17, s1
	v_add3_u32 v18, v177, v18, s1
	v_add3_u32 v16, v176, v16, s1
	v_add3_u32 v15, v178, v15, s1
	v_and_b32_e32 v17, 0xffff0000, v17
	v_and_b32_e32 v18, 0xffff0000, v18
	v_or_b32_sdwa v17, v17, v15 dst_sel:DWORD dst_unused:UNUSED_PAD src0_sel:DWORD src1_sel:WORD_1
	v_or_b32_sdwa v16, v18, v16 dst_sel:DWORD dst_unused:UNUSED_PAD src0_sel:DWORD src1_sel:WORD_1
	global_store_dwordx2 v[6:7], v[16:17], off
	s_waitcnt vmcnt(7)
	v_and_b32_sdwa v21, v183, v14 dst_sel:DWORD dst_unused:UNUSED_PAD src0_sel:WORD_1 src1_sel:DWORD
	v_and_b32_sdwa v22, v181, v14 dst_sel:DWORD dst_unused:UNUSED_PAD src0_sel:WORD_1 src1_sel:DWORD
	v_and_b32_sdwa v15, v182, v14 dst_sel:DWORD dst_unused:UNUSED_PAD src0_sel:WORD_1 src1_sel:DWORD
	v_and_b32_sdwa v20, v180, v14 dst_sel:DWORD dst_unused:UNUSED_PAD src0_sel:WORD_1 src1_sel:DWORD
	v_add3_u32 v21, v183, v21, s1
	v_add3_u32 v22, v181, v22, s1
	v_add3_u32 v20, v180, v20, s1
	v_add3_u32 v15, v182, v15, s1
	v_and_b32_e32 v21, 0xffff0000, v21
	v_and_b32_e32 v22, 0xffff0000, v22
	v_or_b32_sdwa v21, v21, v15 dst_sel:DWORD dst_unused:UNUSED_PAD src0_sel:DWORD src1_sel:WORD_1
	v_or_b32_sdwa v20, v22, v20 dst_sel:DWORD dst_unused:UNUSED_PAD src0_sel:DWORD src1_sel:WORD_1
	global_store_dwordx2 v[6:7], v[20:21], off offset:512
	s_waitcnt vmcnt(7)
	v_and_b32_sdwa v25, v187, v14 dst_sel:DWORD dst_unused:UNUSED_PAD src0_sel:WORD_1 src1_sel:DWORD
	v_and_b32_sdwa v26, v185, v14 dst_sel:DWORD dst_unused:UNUSED_PAD src0_sel:WORD_1 src1_sel:DWORD
	v_and_b32_sdwa v15, v186, v14 dst_sel:DWORD dst_unused:UNUSED_PAD src0_sel:WORD_1 src1_sel:DWORD
	v_and_b32_sdwa v24, v184, v14 dst_sel:DWORD dst_unused:UNUSED_PAD src0_sel:WORD_1 src1_sel:DWORD
	v_add3_u32 v25, v187, v25, s1
	v_add3_u32 v26, v185, v26, s1
	v_add3_u32 v24, v184, v24, s1
	v_add3_u32 v15, v186, v15, s1
	v_and_b32_e32 v25, 0xffff0000, v25
	v_and_b32_e32 v26, 0xffff0000, v26
	v_or_b32_sdwa v25, v25, v15 dst_sel:DWORD dst_unused:UNUSED_PAD src0_sel:DWORD src1_sel:WORD_1
	v_or_b32_sdwa v24, v26, v24 dst_sel:DWORD dst_unused:UNUSED_PAD src0_sel:DWORD src1_sel:WORD_1
	global_store_dwordx2 v[6:7], v[24:25], off offset:1024
	s_waitcnt vmcnt(7)
	v_and_b32_sdwa v29, v191, v14 dst_sel:DWORD dst_unused:UNUSED_PAD src0_sel:WORD_1 src1_sel:DWORD
	v_and_b32_sdwa v30, v189, v14 dst_sel:DWORD dst_unused:UNUSED_PAD src0_sel:WORD_1 src1_sel:DWORD
	v_and_b32_sdwa v15, v190, v14 dst_sel:DWORD dst_unused:UNUSED_PAD src0_sel:WORD_1 src1_sel:DWORD
	v_and_b32_sdwa v28, v188, v14 dst_sel:DWORD dst_unused:UNUSED_PAD src0_sel:WORD_1 src1_sel:DWORD
	v_add3_u32 v29, v191, v29, s1
	v_add3_u32 v30, v189, v30, s1
	v_add3_u32 v28, v188, v28, s1
	v_add3_u32 v15, v190, v15, s1
	v_and_b32_e32 v29, 0xffff0000, v29
	v_and_b32_e32 v30, 0xffff0000, v30
	v_or_b32_sdwa v29, v29, v15 dst_sel:DWORD dst_unused:UNUSED_PAD src0_sel:DWORD src1_sel:WORD_1
	v_or_b32_sdwa v28, v30, v28 dst_sel:DWORD dst_unused:UNUSED_PAD src0_sel:DWORD src1_sel:WORD_1
	global_store_dwordx2 v[6:7], v[28:29], off offset:1536
	s_waitcnt vmcnt(7)
	v_and_b32_sdwa v33, v195, v14 dst_sel:DWORD dst_unused:UNUSED_PAD src0_sel:WORD_1 src1_sel:DWORD
	v_and_b32_sdwa v34, v193, v14 dst_sel:DWORD dst_unused:UNUSED_PAD src0_sel:WORD_1 src1_sel:DWORD
	v_and_b32_sdwa v15, v194, v14 dst_sel:DWORD dst_unused:UNUSED_PAD src0_sel:WORD_1 src1_sel:DWORD
	v_and_b32_sdwa v32, v192, v14 dst_sel:DWORD dst_unused:UNUSED_PAD src0_sel:WORD_1 src1_sel:DWORD
	v_add3_u32 v33, v195, v33, s1
	v_add3_u32 v34, v193, v34, s1
	v_add3_u32 v32, v192, v32, s1
	v_add3_u32 v15, v194, v15, s1
	v_and_b32_e32 v33, 0xffff0000, v33
	v_and_b32_e32 v34, 0xffff0000, v34
	v_or_b32_sdwa v33, v33, v15 dst_sel:DWORD dst_unused:UNUSED_PAD src0_sel:DWORD src1_sel:WORD_1
	v_or_b32_sdwa v32, v34, v32 dst_sel:DWORD dst_unused:UNUSED_PAD src0_sel:DWORD src1_sel:WORD_1
	global_store_dwordx2 v[6:7], v[32:33], off offset:2048
	s_waitcnt vmcnt(7)
	v_and_b32_sdwa v37, v199, v14 dst_sel:DWORD dst_unused:UNUSED_PAD src0_sel:WORD_1 src1_sel:DWORD
	v_and_b32_sdwa v38, v197, v14 dst_sel:DWORD dst_unused:UNUSED_PAD src0_sel:WORD_1 src1_sel:DWORD
	v_and_b32_sdwa v15, v198, v14 dst_sel:DWORD dst_unused:UNUSED_PAD src0_sel:WORD_1 src1_sel:DWORD
	v_and_b32_sdwa v36, v196, v14 dst_sel:DWORD dst_unused:UNUSED_PAD src0_sel:WORD_1 src1_sel:DWORD
	v_add3_u32 v37, v199, v37, s1
	v_add3_u32 v38, v197, v38, s1
	v_add3_u32 v36, v196, v36, s1
	v_add3_u32 v15, v198, v15, s1
	v_and_b32_e32 v37, 0xffff0000, v37
	v_and_b32_e32 v38, 0xffff0000, v38
	v_or_b32_sdwa v37, v37, v15 dst_sel:DWORD dst_unused:UNUSED_PAD src0_sel:DWORD src1_sel:WORD_1
	v_or_b32_sdwa v36, v38, v36 dst_sel:DWORD dst_unused:UNUSED_PAD src0_sel:DWORD src1_sel:WORD_1
	global_store_dwordx2 v[6:7], v[36:37], off offset:2560
	s_waitcnt vmcnt(7)
	v_and_b32_sdwa v41, v203, v14 dst_sel:DWORD dst_unused:UNUSED_PAD src0_sel:WORD_1 src1_sel:DWORD
	v_and_b32_sdwa v42, v201, v14 dst_sel:DWORD dst_unused:UNUSED_PAD src0_sel:WORD_1 src1_sel:DWORD
	v_and_b32_sdwa v15, v202, v14 dst_sel:DWORD dst_unused:UNUSED_PAD src0_sel:WORD_1 src1_sel:DWORD
	v_and_b32_sdwa v40, v200, v14 dst_sel:DWORD dst_unused:UNUSED_PAD src0_sel:WORD_1 src1_sel:DWORD
	v_add3_u32 v41, v203, v41, s1
	v_add3_u32 v42, v201, v42, s1
	v_add3_u32 v40, v200, v40, s1
	v_add3_u32 v15, v202, v15, s1
	v_and_b32_e32 v41, 0xffff0000, v41
	v_and_b32_e32 v42, 0xffff0000, v42
	v_or_b32_sdwa v41, v41, v15 dst_sel:DWORD dst_unused:UNUSED_PAD src0_sel:DWORD src1_sel:WORD_1
	v_or_b32_sdwa v40, v42, v40 dst_sel:DWORD dst_unused:UNUSED_PAD src0_sel:DWORD src1_sel:WORD_1
	global_store_dwordx2 v[6:7], v[40:41], off offset:3072
	s_waitcnt vmcnt(7)
	v_and_b32_sdwa v45, v207, v14 dst_sel:DWORD dst_unused:UNUSED_PAD src0_sel:WORD_1 src1_sel:DWORD
	v_and_b32_sdwa v46, v205, v14 dst_sel:DWORD dst_unused:UNUSED_PAD src0_sel:WORD_1 src1_sel:DWORD
	v_and_b32_sdwa v15, v206, v14 dst_sel:DWORD dst_unused:UNUSED_PAD src0_sel:WORD_1 src1_sel:DWORD
	v_and_b32_sdwa v44, v204, v14 dst_sel:DWORD dst_unused:UNUSED_PAD src0_sel:WORD_1 src1_sel:DWORD
	v_add3_u32 v45, v207, v45, s1
	v_add3_u32 v46, v205, v46, s1
	v_add3_u32 v44, v204, v44, s1
	v_add3_u32 v15, v206, v15, s1
	v_and_b32_e32 v45, 0xffff0000, v45
	v_and_b32_e32 v46, 0xffff0000, v46
	v_or_b32_sdwa v45, v45, v15 dst_sel:DWORD dst_unused:UNUSED_PAD src0_sel:DWORD src1_sel:WORD_1
	v_or_b32_sdwa v44, v46, v44 dst_sel:DWORD dst_unused:UNUSED_PAD src0_sel:DWORD src1_sel:WORD_1
	global_store_dwordx2 v[6:7], v[44:45], off offset:3584
	v_mul_f32_e32 v15, v177, v177
	v_mul_f32_e32 v48, v179, v179
	v_fmac_f32_e32 v15, v176, v176
	v_fmac_f32_e32 v48, v178, v178
	v_add_f32_e32 v15, v15, v48
	v_mul_f32_e32 v49, v181, v181
	v_mul_f32_e32 v48, v183, v183
	v_fmac_f32_e32 v49, v180, v180
	v_fmac_f32_e32 v48, v182, v182
	v_add_f32_e32 v49, v49, v48
	v_add_f32_e32 v15, v15, v49
	v_mul_f32_e32 v49, v185, v185
	v_mul_f32_e32 v48, v187, v187
	v_fmac_f32_e32 v49, v184, v184
	v_fmac_f32_e32 v48, v186, v186
	v_add_f32_e32 v49, v49, v48
	v_add_f32_e32 v15, v15, v49
	v_mul_f32_e32 v49, v189, v189
	v_mul_f32_e32 v48, v191, v191
	v_fmac_f32_e32 v49, v188, v188
	v_fmac_f32_e32 v48, v190, v190
	v_add_f32_e32 v49, v49, v48
	v_add_f32_e32 v15, v15, v49
	v_mul_f32_e32 v49, v193, v193
	v_mul_f32_e32 v48, v195, v195
	v_fmac_f32_e32 v49, v192, v192
	v_fmac_f32_e32 v48, v194, v194
	v_add_f32_e32 v49, v49, v48
	v_add_f32_e32 v15, v15, v49
	v_mul_f32_e32 v49, v197, v197
	v_mul_f32_e32 v48, v199, v199
	v_fmac_f32_e32 v49, v196, v196
	v_fmac_f32_e32 v48, v198, v198
	v_add_f32_e32 v49, v49, v48
	v_add_f32_e32 v15, v15, v49
	v_mul_f32_e32 v49, v201, v201
	v_mul_f32_e32 v48, v203, v203
	v_fmac_f32_e32 v49, v200, v200
	v_fmac_f32_e32 v48, v202, v202
	v_add_f32_e32 v49, v49, v48
	v_add_f32_e32 v15, v15, v49
	v_mul_f32_e32 v49, v205, v205
	v_mul_f32_e32 v48, v207, v207
	v_fmac_f32_e32 v49, v204, v204
	v_fmac_f32_e32 v48, v206, v206
	v_add_f32_e32 v49, v49, v48
	v_add_f32_e32 v15, v15, v49
	ds_bpermute_b32 v50, v8, v15
	s_waitcnt lgkmcnt(0)
	v_add_f32_e32 v15, v15, v50
	ds_bpermute_b32 v50, v9, v15
	s_waitcnt lgkmcnt(0)
	v_add_f32_e32 v15, v15, v50
	ds_bpermute_b32 v50, v10, v15
	s_waitcnt lgkmcnt(0)
	v_add_f32_e32 v15, v15, v50
	ds_bpermute_b32 v50, v11, v15
	s_waitcnt lgkmcnt(0)
	v_add_f32_e32 v15, v15, v50
	ds_bpermute_b32 v50, v12, v15
	s_waitcnt lgkmcnt(0)
	v_add_f32_e32 v15, v15, v50
	ds_bpermute_b32 v50, v13, v15
	s_and_saveexec_b64 s[16:17], s[4:5]
	s_cbranch_execz .LBB0_56
	s_waitcnt lgkmcnt(0)
	v_add_f32_e32 v6, v15, v50
	v_cndmask_b32_e64 v15, 0, v6, s[6:7]
	v_lshl_add_u64 v[6:7], s[14:15], 0, v[0:1]
	global_store_dword v[6:7], v15, off
	s_branch .LBB0_56
